# three grid barriers (GEMM-down to row phase) replaced by 4-workgroup group-local release/acquire syncs; row phases remapped to 160-row groups
# speedup vs baseline: 1.0410x; 1.0107x over previous
.LBB0_264:
.LBB0_322:
	s_cmp_gt_i32 s31, 4
	s_cselect_b64 s[0:1], -1, 0
	s_and_b64 s[4:5], s[6:7], s[0:1]
	s_andn2_b64 vcc, exec, s[4:5]
	s_cbranch_vccnz .LBB0_382
	s_cmpk_eq_i32 s3, 0x100
	s_cbranch_scc1 .Lls3
	s_waitcnt vmcnt(0)
	s_waitcnt vmcnt(0)
	s_barrier
	s_and_saveexec_b64 s[4:5], s[16:17]
	s_cbranch_execz .LBB0_381
	s_add_i32 s6, 0, 0x20160
	v_mov_b32_e32 v1, s6
	s_waitcnt vmcnt(0) expcnt(0) lgkmcnt(0)
	ds_read_b32 v3, v1
	s_add_i32 s6, 0, 0x20164
	v_mov_b32_e32 v1, s6
	ds_read_b32 v1, v1
	s_waitcnt lgkmcnt(1)
	v_cmp_ne_u32_e32 vcc, 0, v3
	s_cbranch_vccnz .LBB0_339
	s_load_dwordx2 s[10:11], s[94:95], 0x4
	s_add_u32 s6, s28, 0x1200
	s_addc_u32 s7, s29, 0
	s_add_u32 s8, s28, 0x1400
	s_addc_u32 s9, s29, 0
	s_waitcnt lgkmcnt(0)
	s_mul_i32 s20, s10, s3
	s_add_u32 s10, s28, 0x1500
	s_mul_i32 s20, s20, s11
	s_addc_u32 s11, s29, 0
	s_add_u32 s12, s28, 0x1600
	s_addc_u32 s13, s29, 0
	s_add_u32 s14, s28, 0x1700
	s_addc_u32 s15, s29, 0
	s_add_u32 s18, s28, 0x1800
	s_addc_u32 s19, s29, 0
	s_add_u32 s24, s28, 0x1900
	s_addc_u32 s25, s29, 0
	s_add_u32 s44, s28, 0x1a00
	s_addc_u32 s45, s29, 0
	s_add_u32 s46, s28, 0x1b00
	s_addc_u32 s47, s29, 0
	s_add_u32 s48, s28, 0x1c00
	s_addc_u32 s49, s29, 0
	s_add_u32 s56, s28, 0x1d00
	s_addc_u32 s57, s29, 0
	s_add_u32 s58, s28, 0x1e00
	s_addc_u32 s59, s29, 0
	s_add_u32 s60, s28, 0x1f00
	s_addc_u32 s61, s29, 0
	s_add_u32 s62, s28, 0x2000
	s_addc_u32 s63, s29, 0
	s_add_u32 s64, s28, 0x2100
	s_addc_u32 s65, s29, 0
	s_add_u32 s66, s28, 0x2200
	s_addc_u32 s67, s29, 0
	s_add_u32 s70, s28, 0x2300
	s_addc_u32 s71, s29, 0
	s_mov_b32 s21, 1
	v_mov_b32_e32 v17, 0
	s_branch .LBB0_327

.LBB0_381:
	s_or_b64 exec, exec, s[4:5]
	s_waitcnt lgkmcnt(0)
	s_barrier
	s_branch .LBB0_382
.Lls3:
	s_and_b32 s4, s2, 7
	s_lshl_b32 s4, s4, 3
	s_bfe_u32 s5, s2, 0x30003
	s_add_i32 s4, s4, s5
	s_lshl_b32 s4, s4, 6
	s_add_u32 s8, s28, s4
	s_addc_u32 s9, s29, 0
	s_mov_b32 s12, 0
	s_and_saveexec_b64 s[10:11], s[16:17]
	s_cbranch_execz .Lls3_join
	v_mov_b32_e32 v1, 0xa000
	v_mov_b32_e32 v2, 1
	global_atomic_add v1, v2, s[8:9]
.Lls3_spin:
	global_load_dword v3, v1, s[8:9] sc1
	s_waitcnt vmcnt(0)
	v_readfirstlane_b32 s13, v3
	s_add_i32 s12, s12, 1
	s_nop 1
	s_cmp_lt_u32 s13, 4
	s_cbranch_scc0 .Lls3_done
	s_sleep 1
	s_cmp_lt_u32 s12, 0x100000
	s_cbranch_scc1 .Lls3_spin
.Lls3_done:
	buffer_inv sc1
	s_waitcnt vmcnt(0)
.Lls3_join:
	s_or_b64 exec, exec, s[10:11]
	s_barrier
.LBB0_382:
	s_cmp_lt_i32 s30, 5
	s_cselect_b64 s[4:5], -1, 0
	s_and_b64 s[4:5], s[4:5], s[0:1]
	s_andn2_b64 vcc, exec, s[4:5]
	s_cbranch_vccnz .LBB0_388
	s_lshl_b32 s0, s2, 3
	s_add_i32 s99, s33, s0
	s_movk_i32 s98, 0x2800
	s_lshl_b32 s100, s3, 3
	s_cmpk_lg_i32 s3, 0x100
	s_cbranch_scc1 .Lls3_gen
	s_and_b32 s0, s2, 7
	s_lshl_b32 s0, s0, 3
	s_bfe_u32 s1, s2, 0x30003
	s_add_i32 s0, s0, s1
	s_mul_i32 s0, s0, 0xa0
	s_lshr_b32 s1, s2, 6
	s_lshl_b32 s1, s1, 3
	s_add_i32 s99, s0, s1
	s_add_i32 s99, s99, s33
	s_add_i32 s98, s0, 0xa0
	s_mov_b32 s100, 32
.Lls3_gen:
	s_mov_b32 s6, s99
	s_cmpk_gt_i32 s6, 0x27ff
	s_cbranch_scc1 .LBB0_388
	s_add_u32 s18, s28, 0x100000
	s_addc_u32 s19, s29, 0
	s_mov_b32 s8, s100
	v_lshlrev_b32_e32 v50, 2, v164
	s_add_u32 s0, s36, 0x1000
	v_mov_b32_e32 v3, 0
	v_or_b32_e32 v4, 0x100, v50
	s_addc_u32 s1, s37, 0
	v_lshlrev_b32_e32 v2, 4, v164
	v_or_b32_e32 v6, 0x200, v50
	v_lshl_add_u64 v[52:53], s[38:39], 0, v[2:3]
	v_lshl_add_u64 v[54:55], s[0:1], 0, v[2:3]
	v_lshlrev_b32_e32 v2, 2, v4
	v_or_b32_e32 v8, 0x300, v50
	v_lshl_add_u64 v[56:57], s[0:1], 0, v[2:3]
	v_lshlrev_b32_e32 v2, 2, v6
	v_lshl_add_u64 v[58:59], s[0:1], 0, v[2:3]
	v_lshlrev_b32_e32 v2, 2, v8
	v_mbcnt_lo_u32_b32 v1, -1, 0
	v_lshl_add_u64 v[60:61], s[0:1], 0, v[2:3]
	v_mbcnt_hi_u32_b32 v2, -1, v1
	v_and_b32_e32 v1, 64, v2
	v_add_u32_e32 v5, 64, v1
	v_xor_b32_e32 v1, 1, v2
	v_cmp_lt_i32_e32 vcc, v1, v5
	v_xor_b32_e32 v7, 2, v2
	s_ashr_i32 s7, s6, 31
	v_cndmask_b32_e32 v1, v2, v1, vcc
	v_cmp_lt_i32_e32 vcc, v7, v5
	s_lshl_b64 s[0:1], s[6:7], 11
	s_add_u32 s0, s28, s0
	v_cndmask_b32_e32 v7, v2, v7, vcc
	v_lshlrev_b32_e32 v51, 2, v7
	v_xor_b32_e32 v7, 4, v2
	v_cmp_lt_i32_e32 vcc, v7, v5
	s_addc_u32 s1, s29, s1
	s_ashr_i32 s9, s8, 31
	v_cndmask_b32_e32 v7, v2, v7, vcc
	v_lshlrev_b32_e32 v64, 2, v7
	v_xor_b32_e32 v7, 8, v2
	v_cmp_lt_i32_e32 vcc, v7, v5
	s_mov_b32 s11, 0
	s_mov_b32 s10, -1
	v_cndmask_b32_e32 v7, v2, v7, vcc
	v_lshlrev_b32_e32 v65, 2, v7
	v_xor_b32_e32 v7, 16, v2
	v_cmp_lt_i32_e32 vcc, v7, v5
	v_lshlrev_b32_e32 v1, 2, v1
	s_lshl_b64 s[12:13], s[8:9], 11
	v_cndmask_b32_e32 v7, v2, v7, vcc
	v_lshlrev_b32_e32 v66, 2, v7
	v_xor_b32_e32 v7, 32, v2
	v_cmp_lt_i32_e32 vcc, v7, v5
	v_lshlrev_b32_e32 v68, 2, v4
	v_lshlrev_b32_e32 v69, 2, v6
	v_cndmask_b32_e32 v2, v2, v7, vcc
	v_lshlrev_b32_e32 v67, 2, v2
	v_lshlrev_b32_e32 v2, 3, v164
	v_lshl_add_u64 v[2:3], s[0:1], 0, v[2:3]
	s_mov_b64 s[0:1], 0x6d00600
	v_lshl_add_u64 v[62:63], v[2:3], 0, s[0:1]
	v_lshlrev_b32_e32 v70, 2, v8
	s_mov_b32 s20, 0xfd800000
	v_mov_b32_e32 v71, 0x358637bd
	s_mov_b32 s21, 0xf800000
	v_mov_b32_e32 v72, 0x260
	s_mov_b32 s22, 0xfc400000
	s_branch .LBB0_386
.LBB0_385:
	v_add_co_u32_e32 v74, vcc, s20, v62
	s_and_b64 s[0:1], s[0:1], exec
	s_nop 0
	v_addc_co_u32_e32 v75, vcc, -1, v63, vcc
	global_load_dwordx2 v[78:79], v[74:75], off offset:-1536 nt
	global_load_dwordx2 v[80:81], v[74:75], off offset:-1024 nt
	global_load_dwordx2 v[82:83], v[74:75], off offset:-512 nt
	global_load_dwordx2 v[84:85], v[74:75], off nt
	s_cselect_b32 s1, s7, 0
	s_cselect_b32 s0, s6, s23
	s_cselect_b32 s14, s53, s55
	s_cselect_b32 s15, s52, s54
	s_lshl_b64 s[0:1], s[0:1], 12
	s_add_u32 s0, s15, s0
	s_addc_u32 s1, s14, s1
	global_load_dwordx4 v[74:77], v73, s[0:1]
	s_add_u32 s6, s6, s8
	s_addc_u32 s7, s7, s9
	s_cmp_lt_i32 s6, s98
	s_waitcnt vmcnt(0)
	v_and_b32_e32 v91, 0xffff0000, v78
	v_and_b32_e32 v93, 0xffff0000, v79
	v_lshlrev_b32_e32 v90, 16, v78
	v_lshlrev_b32_e32 v103, 16, v84
	v_lshlrev_b32_e32 v92, 16, v79
	v_and_b32_e32 v97, 0xffff0000, v81
	v_and_b32_e32 v96, 0xffff0000, v80
	v_lshlrev_b32_e32 v98, 16, v82
	v_and_b32_e32 v99, 0xffff0000, v82
	v_mul_f32_e32 v78, v93, v93
	v_mul_f32_e32 v82, v91, v91
	v_mov_b32_e32 v79, v103
	v_lshlrev_b32_e32 v95, 16, v81
	v_lshlrev_b32_e32 v94, 16, v80
	v_lshlrev_b32_e32 v100, 16, v83
	v_and_b32_e32 v101, 0xffff0000, v83
	v_pk_mul_f32 v[80:81], v[96:97], v[96:97]
	v_pk_fma_f32 v[88:89], v[92:93], v[92:93], v[78:79] op_sel_hi:[1,1,0]
	v_pk_fma_f32 v[82:83], v[90:91], v[90:91], v[82:83] op_sel_hi:[1,1,0]
	v_and_b32_e32 v105, 0xffff0000, v84
	v_lshlrev_b32_e32 v106, 16, v85
	v_and_b32_e32 v107, 0xffff0000, v85
	v_mul_f32_e32 v84, v99, v99
	v_mul_f32_e32 v86, v101, v101
	v_pk_fma_f32 v[80:81], v[94:95], v[94:95], v[80:81]
	v_mov_b32_e32 v102, v82
	v_mov_b32_e32 v78, v88
	v_mul_f32_e32 v104, v105, v105
	v_mul_f32_e32 v108, v106, v106
	v_mul_f32_e32 v109, v107, v107
	v_pk_fma_f32 v[84:85], v[98:99], v[98:99], v[84:85] op_sel_hi:[1,1,0]
	v_pk_fma_f32 v[86:87], v[100:101], v[100:101], v[86:87] op_sel_hi:[1,1,0]
	v_pk_add_f32 v[82:83], v[82:83], v[88:89]
	v_pk_add_f32 v[80:81], v[80:81], v[80:81] op_sel:[0,1] op_sel_hi:[1,0]
	v_pk_mul_f32 v[78:79], v[102:103], v[78:79]
	v_mov_b32_e32 v85, v108
	v_mov_b32_e32 v87, v109
	v_mov_b32_e32 v81, v104
	v_mov_b32_e32 v83, v79
	v_pk_add_f32 v[84:85], v[84:85], v[86:87]
	v_pk_add_f32 v[78:79], v[82:83], v[80:81]
	v_mov_b32_e32 v108, v94
	v_pk_add_f32 v[78:79], v[78:79], v[84:85]
	v_mov_b32_e32 v109, v96
	v_add_f32_e32 v102, v78, v79
	global_load_dwordx4 v[78:81], v73, s[0:1] offset:1024
	global_load_dwordx4 v[82:85], v73, s[0:1] offset:2048
	global_load_dwordx4 v[86:89], v73, s[0:1] offset:3072
	ds_bpermute_b32 v104, v1, v102
	v_mov_b32_e32 v96, v95
	s_waitcnt lgkmcnt(0)
	v_add_f32_e32 v73, v102, v104
	ds_bpermute_b32 v102, v51, v73
	s_waitcnt lgkmcnt(0)
	v_add_f32_e32 v73, v73, v102
	ds_bpermute_b32 v102, v64, v73
	s_waitcnt lgkmcnt(0)
	v_add_f32_e32 v73, v73, v102
	ds_bpermute_b32 v102, v65, v73
	s_waitcnt lgkmcnt(0)
	v_add_f32_e32 v73, v73, v102
	ds_bpermute_b32 v102, v66, v73
	s_waitcnt lgkmcnt(0)
	v_add_f32_e32 v73, v73, v102
	ds_bpermute_b32 v102, v67, v73
	s_waitcnt lgkmcnt(0)
	v_add_f32_e32 v73, v73, v102
	v_fmamk_f32 v73, v73, 0x3a800000, v71
	v_mul_f32_e32 v102, 0x4f800000, v73
	v_cmp_gt_f32_e32 vcc, s21, v73
	s_nop 1
	v_cndmask_b32_e32 v73, v73, v102, vcc
	v_sqrt_f32_e32 v102, v73
	s_nop 0
	v_add_u32_e32 v94, -1, v102
	v_add_u32_e32 v95, 1, v102
	v_fma_f32 v104, -v94, v102, v73
	v_fma_f32 v110, -v95, v102, v73
	v_cmp_ge_f32_e64 s[0:1], 0, v104
	v_mov_b32_e32 v104, v103
	s_nop 0
	v_cndmask_b32_e64 v94, v102, v94, s[0:1]
	v_cmp_lt_f32_e64 s[0:1], 0, v110
	s_nop 1
	v_cndmask_b32_e64 v94, v94, v95, s[0:1]
	v_mul_f32_e32 v95, 0x37800000, v94
	v_cndmask_b32_e32 v94, v94, v95, vcc
	v_cmp_class_f32_e32 vcc, v73, v72
	s_nop 1
	v_cndmask_b32_e32 v73, v94, v73, vcc
	v_div_scale_f32 v94, s[0:1], v73, v73, 1.0
	v_rcp_f32_e32 v95, v94
	v_div_scale_f32 v102, vcc, 1.0, v73, 1.0
	v_fma_f32 v103, -v94, v95, 1.0
	v_fmac_f32_e32 v95, v103, v95
	v_mul_f32_e32 v103, v102, v95
	v_fma_f32 v110, -v94, v103, v102
	v_fmac_f32_e32 v103, v110, v95
	v_fma_f32 v94, -v94, v103, v102
	v_div_fmas_f32 v94, v94, v95, v103
	v_div_fixup_f32 v94, v94, v73, 1.0
	v_pk_mul_f32 v[90:91], v[94:95], v[90:91] op_sel_hi:[0,1]
	v_pk_mul_f32 v[92:93], v[94:95], v[92:93] op_sel_hi:[0,1]
	v_pk_mul_f32 v[102:103], v[94:95], v[108:109] op_sel_hi:[0,1]
	v_pk_mul_f32 v[96:97], v[94:95], v[96:97] op_sel_hi:[0,1]
	v_pk_mul_f32 v[98:99], v[94:95], v[98:99] op_sel_hi:[0,1]
	v_pk_mul_f32 v[100:101], v[94:95], v[100:101] op_sel_hi:[0,1]
	v_pk_mul_f32 v[104:105], v[104:105], v[94:95] op_sel_hi:[1,0]
	v_pk_mul_f32 v[94:95], v[106:107], v[94:95] op_sel_hi:[1,0]
	v_pk_fma_f32 v[76:77], v[16:17], v[92:93], v[76:77]
	v_pk_fma_f32 v[74:75], v[14:15], v[90:91], v[74:75]
	s_waitcnt vmcnt(2)
	v_pk_fma_f32 v[80:81], v[28:29], v[96:97], v[80:81]
	v_pk_fma_f32 v[78:79], v[26:27], v[102:103], v[78:79]
	s_waitcnt vmcnt(0)
	v_pk_fma_f32 v[88:89], v[24:25], v[94:95], v[88:89]
	v_pk_mul_f32 v[90:91], v[76:77], v[76:77]
	v_pk_mul_f32 v[92:93], v[74:75], v[74:75]
	v_pk_mul_f32 v[94:95], v[80:81], v[80:81]
	v_pk_mul_f32 v[96:97], v[78:79], v[78:79]
	v_pk_fma_f32 v[84:85], v[32:33], v[100:101], v[84:85]
	v_pk_fma_f32 v[82:83], v[30:31], v[98:99], v[82:83]
	v_pk_mov_b32 v[102:103], v[92:93], v[90:91] op_sel:[1,0]
	v_mov_b32_e32 v93, v91
	v_pk_mov_b32 v[90:91], v[96:97], v[94:95] op_sel:[1,0]
	v_mov_b32_e32 v97, v95
	v_mul_f32_e32 v98, v82, v82
	v_mul_f32_e32 v100, v84, v84
	v_pk_add_f32 v[92:93], v[102:103], v[92:93]
	v_pk_add_f32 v[90:91], v[90:91], v[96:97]
	v_pk_fma_f32 v[86:87], v[22:23], v[104:105], v[86:87]
	v_pk_fma_f32 v[94:95], v[82:83], v[82:83], v[98:99] op_sel_hi:[1,1,0]
	v_pk_fma_f32 v[98:99], v[84:85], v[84:85], v[100:101] op_sel_hi:[1,1,0]
	v_pk_add_f32 v[92:93], v[92:93], v[92:93] op_sel_hi:[0,1]
	v_pk_add_f32 v[90:91], v[90:91], v[90:91] op_sel_hi:[0,1]
	v_mul_f32_e32 v94, v86, v86
	v_mul_f32_e32 v98, v87, v87
	v_mul_f32_e32 v92, v88, v88
	v_mul_f32_e32 v90, v89, v89
	v_pk_add_f32 v[94:95], v[94:95], v[98:99]
	v_pk_add_f32 v[90:91], v[92:93], v[90:91]
	v_cvt_pk_bf16_f32 v93, v76, v77
	v_pk_add_f32 v[90:91], v[94:95], v[90:91]
	v_cvt_pk_bf16_f32 v94, v78, v79
	v_add_f32_e32 v73, v90, v91
	ds_bpermute_b32 v90, v1, v73
	v_cvt_pk_bf16_f32 v95, v80, v81
	v_cvt_pk_bf16_f32 v97, v84, v85
	v_cvt_pk_bf16_f32 v98, v86, v87
	v_cvt_pk_bf16_f32 v99, v88, v89
	s_waitcnt lgkmcnt(0)
	v_add_f32_e32 v73, v73, v90
	ds_bpermute_b32 v90, v51, v73
	s_waitcnt lgkmcnt(0)
	v_add_f32_e32 v73, v73, v90
	ds_bpermute_b32 v90, v64, v73
	s_waitcnt lgkmcnt(0)
	v_add_f32_e32 v73, v73, v90
	ds_bpermute_b32 v92, v65, v73
	v_add_co_u32_e32 v90, vcc, s22, v62
	s_waitcnt lgkmcnt(0)
	v_add_f32_e32 v73, v73, v92
	ds_bpermute_b32 v96, v66, v73
	v_addc_co_u32_e32 v91, vcc, -1, v63, vcc
	v_cvt_pk_bf16_f32 v92, v74, v75
	s_waitcnt lgkmcnt(0)
	v_add_f32_e32 v73, v73, v96
	ds_bpermute_b32 v100, v67, v73
	v_cvt_pk_bf16_f32 v96, v82, v83
	global_store_dwordx2 v[62:63], v[92:93], off offset:-1536
	global_store_dwordx2 v[62:63], v[94:95], off offset:-1024
	global_store_dwordx2 v[62:63], v[96:97], off offset:-512
	global_store_dwordx2 v[62:63], v[98:99], off
	v_lshl_add_u64 v[62:63], v[62:63], 0, s[12:13]
	s_waitcnt lgkmcnt(0)
	v_add_f32_e32 v73, v73, v100
	v_fmamk_f32 v73, v73, 0x3a800000, v71
	v_mul_f32_e32 v100, 0x4f800000, v73
	v_cmp_gt_f32_e32 vcc, s21, v73
	s_nop 1
	v_cndmask_b32_e32 v73, v73, v100, vcc
	v_sqrt_f32_e32 v100, v73
	s_nop 0
	v_add_u32_e32 v92, -1, v100
	v_add_u32_e32 v93, 1, v100
	v_fma_f32 v94, -v92, v100, v73
	v_fma_f32 v95, -v93, v100, v73
	v_cmp_ge_f32_e64 s[0:1], 0, v94
	s_nop 1
	v_cndmask_b32_e64 v92, v100, v92, s[0:1]
	v_cmp_lt_f32_e64 s[0:1], 0, v95
	s_nop 1
	v_cndmask_b32_e64 v92, v92, v93, s[0:1]
	v_mul_f32_e32 v93, 0x37800000, v92
	v_cndmask_b32_e32 v92, v92, v93, vcc
	v_cmp_class_f32_e32 vcc, v73, v72
	s_nop 1
	v_cndmask_b32_e32 v73, v92, v73, vcc
	v_div_scale_f32 v92, s[0:1], v73, v73, 1.0
	v_rcp_f32_e32 v93, v92
	v_div_scale_f32 v94, vcc, 1.0, v73, 1.0
	v_fma_f32 v95, -v92, v93, 1.0
	v_fmac_f32_e32 v93, v95, v93
	v_mul_f32_e32 v95, v94, v93
	v_fma_f32 v96, -v92, v95, v94
	v_fmac_f32_e32 v95, v96, v93
	v_fma_f32 v92, -v92, v95, v94
	v_div_fmas_f32 v92, v92, v93, v95
	v_div_fixup_f32 v92, v92, v73, 1.0
	v_pk_mul_f32 v[74:75], v[74:75], v[92:93] op_sel_hi:[1,0]
	v_pk_mul_f32 v[76:77], v[76:77], v[92:93] op_sel_hi:[1,0]
	v_pk_mul_f32 v[78:79], v[78:79], v[92:93] op_sel_hi:[1,0]
	v_pk_mul_f32 v[80:81], v[80:81], v[92:93] op_sel_hi:[1,0]
	v_pk_mul_f32 v[82:83], v[82:83], v[92:93] op_sel_hi:[1,0]
	v_pk_mul_f32 v[84:85], v[84:85], v[92:93] op_sel_hi:[1,0]
	v_pk_fma_f32 v[76:77], v[36:37], v[76:77], v[20:21]
	v_pk_fma_f32 v[74:75], v[34:35], v[74:75], v[18:19]
	v_pk_fma_f32 v[80:81], v[40:41], v[80:81], v[4:5]
	v_pk_fma_f32 v[78:79], v[38:39], v[78:79], v[2:3]
	v_pk_fma_f32 v[84:85], v[44:45], v[84:85], v[12:13]
	v_pk_fma_f32 v[82:83], v[42:43], v[82:83], v[10:11]
	v_cvt_pk_bf16_f32 v74, v74, v75
	v_cvt_pk_bf16_f32 v75, v76, v77
	v_cvt_pk_bf16_f32 v76, v78, v79
	v_cvt_pk_bf16_f32 v77, v80, v81
	v_cvt_pk_bf16_f32 v78, v82, v83
	v_cvt_pk_bf16_f32 v79, v84, v85
	global_store_dwordx2 v[90:91], v[74:75], off offset:-1536
	global_store_dwordx2 v[90:91], v[76:77], off offset:-1024
	global_store_dwordx2 v[90:91], v[78:79], off offset:-512
	v_pk_mul_f32 v[74:75], v[86:87], v[92:93] op_sel_hi:[1,0]
	v_pk_mul_f32 v[76:77], v[88:89], v[92:93] op_sel_hi:[1,0]
	v_pk_fma_f32 v[74:75], v[46:47], v[74:75], v[6:7]
	v_pk_fma_f32 v[76:77], v[48:49], v[76:77], v[8:9]
	v_cvt_pk_bf16_f32 v74, v74, v75
	v_cvt_pk_bf16_f32 v75, v76, v77
	global_store_dwordx2 v[90:91], v[74:75], off
	s_cbranch_scc0 .LBB0_388

.LBB0_841:
	s_cmp_gt_i32 s31, 8
	s_cselect_b64 s[0:1], -1, 0
	s_and_b64 s[4:5], s[4:5], s[0:1]
	s_andn2_b64 vcc, exec, s[4:5]
	s_cbranch_vccnz .LBB0_901
	s_cmpk_eq_i32 s3, 0x100
	s_cbranch_scc1 .Lls7
	s_waitcnt vmcnt(0)
	s_waitcnt vmcnt(0)
	s_barrier
	s_and_saveexec_b64 s[4:5], s[16:17]
	s_cbranch_execz .LBB0_900
	s_add_i32 s6, 0, 0x20160
	v_mov_b32_e32 v1, s6
	s_waitcnt vmcnt(0) expcnt(0) lgkmcnt(0)
	ds_read_b32 v3, v1
	s_add_i32 s6, 0, 0x20164
	v_mov_b32_e32 v1, s6
	ds_read_b32 v1, v1
	s_waitcnt lgkmcnt(1)
	v_cmp_ne_u32_e32 vcc, 0, v3
	s_cbranch_vccnz .LBB0_858
	s_load_dwordx2 s[10:11], s[94:95], 0x4
	s_add_u32 s6, s28, 0x1200
	s_addc_u32 s7, s29, 0
	s_add_u32 s8, s28, 0x1400
	s_addc_u32 s9, s29, 0
	s_waitcnt lgkmcnt(0)
	s_mul_i32 s26, s10, s3
	s_add_u32 s10, s28, 0x1500
	s_mul_i32 s26, s26, s11
	s_addc_u32 s11, s29, 0
	s_add_u32 s12, s28, 0x1600
	s_addc_u32 s13, s29, 0
	s_add_u32 s14, s28, 0x1700
	s_addc_u32 s15, s29, 0
	s_add_u32 s18, s28, 0x1800
	s_addc_u32 s19, s29, 0
	s_add_u32 s20, s28, 0x1900
	s_addc_u32 s21, s29, 0
	s_add_u32 s22, s28, 0x1a00
	s_addc_u32 s23, s29, 0
	s_add_u32 s24, s28, 0x1b00
	s_addc_u32 s25, s29, 0
	s_add_u32 s44, s28, 0x1c00
	s_addc_u32 s45, s29, 0
	s_add_u32 s46, s28, 0x1d00
	s_addc_u32 s47, s29, 0
	s_add_u32 s48, s28, 0x1e00
	s_addc_u32 s49, s29, 0
	s_add_u32 s50, s28, 0x1f00
	s_addc_u32 s51, s29, 0
	s_add_u32 s52, s28, 0x2000
	s_addc_u32 s53, s29, 0
	s_add_u32 s54, s28, 0x2100
	s_addc_u32 s55, s29, 0
	s_add_u32 s56, s28, 0x2200
	s_addc_u32 s57, s29, 0
	s_add_u32 s58, s28, 0x2300
	s_addc_u32 s59, s29, 0
	s_mov_b32 s27, 1
	v_mov_b32_e32 v17, 0
	s_branch .LBB0_846

.Lls7:
	s_and_b32 s4, s2, 7
	s_lshl_b32 s4, s4, 3
	s_bfe_u32 s5, s2, 0x30003
	s_add_i32 s4, s4, s5
	s_lshl_b32 s4, s4, 6
	s_add_u32 s8, s28, s4
	s_addc_u32 s9, s29, 0
	s_mov_b32 s12, 0
	s_and_saveexec_b64 s[10:11], s[16:17]
	s_cbranch_execz .Lls7_join
	v_mov_b32_e32 v1, 0x9000
	v_mov_b32_e32 v2, 1
	global_atomic_add v1, v2, s[8:9]

.LBB0_901:
	s_cmp_lt_i32 s30, 9
	s_cselect_b64 s[4:5], -1, 0
	s_and_b64 s[4:5], s[4:5], s[0:1]
	s_andn2_b64 vcc, exec, s[4:5]
	s_cbranch_vccnz .LBB0_907
	s_lshl_b32 s0, s2, 3
	s_add_i32 s99, s33, s0
	s_movk_i32 s98, 0x2800
	s_lshl_b32 s100, s3, 3
	s_cmpk_lg_i32 s3, 0x100
	s_cbranch_scc1 .Lls7_gen
	s_and_b32 s0, s2, 7
	s_lshl_b32 s0, s0, 3
	s_bfe_u32 s1, s2, 0x30003
	s_add_i32 s0, s0, s1
	s_mul_i32 s0, s0, 0xa0
	s_lshr_b32 s1, s2, 6
	s_lshl_b32 s1, s1, 3
	s_add_i32 s99, s0, s1
	s_add_i32 s99, s99, s33
	s_add_i32 s98, s0, 0xa0
	s_mov_b32 s100, 32
.Lls7_gen:
	s_mov_b32 s6, s99
	s_cmpk_gt_i32 s6, 0x27ff
	s_cbranch_scc1 .LBB0_907
	s_add_u32 s20, s28, 0x100000
	s_addc_u32 s21, s29, 0
	s_mov_b32 s8, s100
	s_add_u32 s0, s38, 0x1000
	s_addc_u32 s1, s39, 0
	v_lshlrev_b32_e32 v2, 2, v164
	s_add_u32 s10, s36, 0x2000
	v_mov_b32_e32 v5, 0
	v_or_b32_e32 v6, 0x100, v2
	s_addc_u32 s11, s37, 0
	v_lshlrev_b32_e32 v4, 4, v164
	v_or_b32_e32 v8, 0x200, v2
	v_lshl_add_u64 v[50:51], s[0:1], 0, v[4:5]
	v_lshl_add_u64 v[52:53], s[10:11], 0, v[4:5]
	v_lshlrev_b32_e32 v4, 2, v6
	v_mbcnt_lo_u32_b32 v1, -1, 0
	v_or_b32_e32 v10, 0x300, v2
	v_lshl_add_u64 v[54:55], s[0:1], 0, v[4:5]
	v_lshl_add_u64 v[56:57], s[10:11], 0, v[4:5]
	v_lshlrev_b32_e32 v4, 2, v8
	v_mbcnt_hi_u32_b32 v3, -1, v1
	v_lshl_add_u64 v[58:59], s[0:1], 0, v[4:5]
	v_lshl_add_u64 v[60:61], s[10:11], 0, v[4:5]
	v_lshlrev_b32_e32 v4, 2, v10
	v_and_b32_e32 v1, 64, v3
	v_lshl_add_u64 v[62:63], s[0:1], 0, v[4:5]
	v_lshl_add_u64 v[64:65], s[10:11], 0, v[4:5]
	v_add_u32_e32 v4, 64, v1
	v_xor_b32_e32 v1, 1, v3
	v_cmp_lt_i32_e32 vcc, v1, v4
	v_xor_b32_e32 v7, 2, v3
	s_ashr_i32 s7, s6, 31
	v_cndmask_b32_e32 v1, v3, v1, vcc
	v_cmp_lt_i32_e32 vcc, v7, v4
	s_lshl_b64 s[0:1], s[6:7], 11
	s_add_u32 s0, s28, s0
	v_cndmask_b32_e32 v7, v3, v7, vcc
	v_lshlrev_b32_e32 v70, 2, v7
	v_xor_b32_e32 v7, 4, v3
	v_cmp_lt_i32_e32 vcc, v7, v4
	s_addc_u32 s1, s29, s1
	s_ashr_i32 s9, s8, 31
	v_cndmask_b32_e32 v7, v3, v7, vcc
	v_lshlrev_b32_e32 v71, 2, v7
	v_xor_b32_e32 v7, 8, v3
	v_cmp_lt_i32_e32 vcc, v7, v4
	s_mov_b32 s11, 0
	s_mov_b32 s10, -1
	v_cndmask_b32_e32 v7, v3, v7, vcc
	v_lshlrev_b32_e32 v72, 2, v7
	v_xor_b32_e32 v7, 16, v3
	v_cmp_lt_i32_e32 vcc, v7, v4
	v_lshlrev_b32_e32 v1, 2, v1
	s_lshl_b64 s[12:13], s[8:9], 11
	v_cndmask_b32_e32 v7, v3, v7, vcc
	v_lshlrev_b32_e32 v73, 2, v7
	v_xor_b32_e32 v7, 32, v3
	v_cmp_lt_i32_e32 vcc, v7, v4
	v_lshlrev_b32_e32 v4, 3, v164
	v_lshl_add_u64 v[4:5], s[0:1], 0, v[4:5]
	v_cndmask_b32_e32 v3, v3, v7, vcc
	s_mov_b64 s[0:1], 0x4500000
	v_lshlrev_b32_e32 v74, 2, v3
	v_lshl_add_u64 v[66:67], v[4:5], 0, s[0:1]
	v_lshlrev_b32_e32 v75, 2, v2
	v_lshlrev_b32_e32 v76, 2, v6
	v_lshlrev_b32_e32 v77, 2, v8
	v_lshlrev_b32_e32 v78, 2, v10
	v_mov_b32_e32 v79, 0x358637bd
	s_mov_b32 s7, 0xf800000
	v_mov_b32_e32 v80, 0x260
	s_mov_b32 s9, 0xfec00000
	s_mov_b32 s22, 0xfec01000
	s_branch .LBB0_905
.LBB0_904:
	global_load_dwordx2 v[82:83], v[66:67], off nt
	global_load_dwordx2 v[84:85], v[66:67], off offset:512 nt
	global_load_dwordx2 v[86:87], v[66:67], off offset:1024 nt
	global_load_dwordx2 v[88:89], v[66:67], off offset:1536 nt
	v_add_co_u32_e32 v68, vcc, 0x2800000, v66
	s_add_i32 s6, s6, s8
	s_nop 0
	v_addc_co_u32_e32 v69, vcc, 0, v67, vcc
	global_load_dwordx2 v[90:91], v[68:69], off nt
	global_load_dwordx2 v[92:93], v[68:69], off offset:512 nt
	global_load_dwordx2 v[94:95], v[68:69], off offset:1024 nt
	global_load_dwordx2 v[96:97], v[68:69], off offset:1536 nt
	s_cmp_lt_i32 s6, s98
	s_waitcnt vmcnt(0)
	v_lshlrev_b32_e32 v98, 16, v82
	v_and_b32_e32 v99, 0xffff0000, v82
	v_lshlrev_b32_e32 v82, 16, v83
	v_and_b32_e32 v83, 0xffff0000, v83
	v_lshlrev_b32_e32 v101, 16, v85
	v_lshlrev_b32_e32 v100, 16, v84
	v_and_b32_e32 v85, 0xffff0000, v85
	v_and_b32_e32 v84, 0xffff0000, v84
	v_and_b32_e32 v103, 0xffff0000, v86
	v_lshlrev_b32_e32 v105, 16, v88
	v_and_b32_e32 v107, 0xffff0000, v88
	v_mul_f32_e32 v104, v83, v83
	v_mul_f32_e32 v106, v99, v99
	v_lshlrev_b32_e32 v102, 16, v86
	v_lshlrev_b32_e32 v86, 16, v87
	v_and_b32_e32 v87, 0xffff0000, v87
	v_pk_mul_f32 v[108:109], v[84:85], v[84:85]
	v_mov_b32_e32 v111, v105
	v_mul_f32_e32 v110, v103, v103
	v_pk_fma_f32 v[114:115], v[82:83], v[82:83], v[104:105] op_sel_hi:[1,1,0]
	v_pk_fma_f32 v[116:117], v[98:99], v[98:99], v[106:107] op_sel_hi:[1,1,0]
	v_lshlrev_b32_e32 v88, 16, v89
	v_and_b32_e32 v89, 0xffff0000, v89
	v_mul_f32_e32 v112, v87, v87
	v_pk_fma_f32 v[108:109], v[100:101], v[100:101], v[108:109]
	v_pk_fma_f32 v[118:119], v[102:103], v[102:103], v[110:111] op_sel_hi:[1,1,0]
	v_mov_b32_e32 v104, v116
	v_mov_b32_e32 v110, v114
	v_mul_f32_e32 v81, v107, v107
	v_mul_f32_e32 v120, v88, v88
	v_mul_f32_e32 v121, v89, v89
	v_pk_fma_f32 v[112:113], v[86:87], v[86:87], v[112:113] op_sel_hi:[1,1,0]
	v_pk_add_f32 v[114:115], v[116:117], v[114:115]
	v_pk_add_f32 v[108:109], v[108:109], v[108:109] op_sel:[0,1] op_sel_hi:[1,0]
	v_pk_mul_f32 v[110:111], v[104:105], v[110:111]
	v_mov_b32_e32 v119, v120
	v_mov_b32_e32 v113, v121
	v_mov_b32_e32 v109, v81
	v_mov_b32_e32 v115, v111
	v_pk_add_f32 v[112:113], v[118:119], v[112:113]
	v_pk_add_f32 v[108:109], v[114:115], v[108:109]
	v_mov_b32_e32 v106, v105
	v_pk_add_f32 v[108:109], v[108:109], v[112:113]
	v_and_b32_e32 v105, 0xffff0000, v92
	v_add_f32_e32 v81, v108, v109
	ds_bpermute_b32 v104, v1, v81
	v_mov_b32_e32 v108, v100
	v_mov_b32_e32 v109, v84
	v_mov_b32_e32 v84, v101
	v_lshlrev_b32_e32 v100, 16, v90
	s_waitcnt lgkmcnt(0)
	v_add_f32_e32 v81, v81, v104
	ds_bpermute_b32 v104, v70, v81
	v_and_b32_e32 v101, 0xffff0000, v90
	v_lshlrev_b32_e32 v90, 16, v91
	v_and_b32_e32 v91, 0xffff0000, v91
	v_and_b32_e32 v111, 0xffff0000, v94
	s_waitcnt lgkmcnt(0)
	v_add_f32_e32 v81, v81, v104
	ds_bpermute_b32 v104, v71, v81
	v_and_b32_e32 v113, 0xffff0000, v96
	s_waitcnt lgkmcnt(0)
	v_add_f32_e32 v81, v81, v104
	ds_bpermute_b32 v104, v72, v81
	s_waitcnt lgkmcnt(0)
	v_add_f32_e32 v81, v81, v104
	ds_bpermute_b32 v110, v73, v81
	v_lshlrev_b32_e32 v104, 16, v92
	v_lshlrev_b32_e32 v92, 16, v93
	v_and_b32_e32 v93, 0xffff0000, v93
	s_waitcnt lgkmcnt(0)
	v_add_f32_e32 v81, v81, v110
	ds_bpermute_b32 v112, v74, v81
	v_lshlrev_b32_e32 v110, 16, v94
	v_lshlrev_b32_e32 v94, 16, v95
	v_and_b32_e32 v95, 0xffff0000, v95
	s_waitcnt lgkmcnt(0)
	v_add_f32_e32 v81, v81, v112
	v_fmamk_f32 v81, v81, 0x3a800000, v79
	v_mul_f32_e32 v112, 0x4f800000, v81
	v_cmp_gt_f32_e32 vcc, s7, v81
	s_nop 1
	v_cndmask_b32_e32 v81, v81, v112, vcc
	v_sqrt_f32_e32 v114, v81
	v_lshlrev_b32_e32 v112, 16, v96
	v_lshlrev_b32_e32 v96, 16, v97
	v_and_b32_e32 v97, 0xffff0000, v97
	v_add_u32_e32 v115, -1, v114
	v_add_u32_e32 v116, 1, v114
	v_fma_f32 v117, -v115, v114, v81
	v_fma_f32 v118, -v116, v114, v81
	v_cmp_ge_f32_e64 s[0:1], 0, v117
	s_nop 1
	v_cndmask_b32_e64 v114, v114, v115, s[0:1]
	v_cmp_lt_f32_e64 s[0:1], 0, v118
	s_nop 1
	v_cndmask_b32_e64 v114, v114, v116, s[0:1]
	v_mul_f32_e32 v115, 0x37800000, v114
	v_cndmask_b32_e32 v114, v114, v115, vcc
	v_cmp_class_f32_e32 vcc, v81, v80
	s_nop 1
	v_cndmask_b32_e32 v81, v114, v81, vcc
	v_div_scale_f32 v114, s[0:1], v81, v81, 1.0
	v_rcp_f32_e32 v115, v114
	v_div_scale_f32 v116, vcc, 1.0, v81, 1.0
	v_fma_f32 v117, -v114, v115, 1.0
	v_fmac_f32_e32 v115, v117, v115
	v_mul_f32_e32 v117, v116, v115
	v_fma_f32 v118, -v114, v117, v116
	v_fmac_f32_e32 v117, v118, v115
	v_fma_f32 v114, -v114, v117, v116
	v_div_fmas_f32 v114, v114, v115, v117
	v_div_fixup_f32 v114, v114, v81, 1.0
	v_pk_mul_f32 v[98:99], v[114:115], v[98:99] op_sel_hi:[0,1]
	v_pk_mul_f32 v[82:83], v[114:115], v[82:83] op_sel_hi:[0,1]
	v_pk_mul_f32 v[108:109], v[114:115], v[108:109] op_sel_hi:[0,1]
	v_pk_mul_f32 v[84:85], v[114:115], v[84:85] op_sel_hi:[0,1]
	v_pk_mul_f32 v[102:103], v[114:115], v[102:103] op_sel_hi:[0,1]
	v_pk_mul_f32 v[86:87], v[114:115], v[86:87] op_sel_hi:[0,1]
	v_pk_fma_f32 v[82:83], v[20:21], v[82:83], v[90:91]
	v_pk_fma_f32 v[90:91], v[18:19], v[98:99], v[100:101]
	v_pk_fma_f32 v[84:85], v[28:29], v[84:85], v[92:93]
	v_pk_fma_f32 v[92:93], v[26:27], v[108:109], v[104:105]
	v_pk_fma_f32 v[86:87], v[16:17], v[86:87], v[94:95]
	v_pk_fma_f32 v[94:95], v[14:15], v[102:103], v[110:111]
	v_pk_mul_f32 v[98:99], v[82:83], v[82:83]
	v_pk_mul_f32 v[100:101], v[90:91], v[90:91]
	v_pk_mul_f32 v[102:103], v[84:85], v[84:85]
	v_pk_mul_f32 v[104:105], v[92:93], v[92:93]
	v_pk_mul_f32 v[106:107], v[106:107], v[114:115] op_sel_hi:[1,0]
	v_pk_mul_f32 v[88:89], v[88:89], v[114:115] op_sel_hi:[1,0]
	v_pk_mov_b32 v[110:111], v[100:101], v[98:99] op_sel:[1,0]
	v_mov_b32_e32 v101, v99
	v_pk_mov_b32 v[98:99], v[104:105], v[102:103] op_sel:[1,0]
	v_mov_b32_e32 v105, v103
	v_pk_fma_f32 v[88:89], v[32:33], v[88:89], v[96:97]
	v_pk_fma_f32 v[96:97], v[30:31], v[106:107], v[112:113]
	v_mul_f32_e32 v106, v94, v94
	v_mul_f32_e32 v108, v86, v86
	v_pk_add_f32 v[100:101], v[110:111], v[100:101]
	v_pk_add_f32 v[98:99], v[98:99], v[104:105]
	v_pk_fma_f32 v[102:103], v[94:95], v[94:95], v[106:107] op_sel_hi:[1,1,0]
	v_pk_fma_f32 v[106:107], v[86:87], v[86:87], v[108:109] op_sel_hi:[1,1,0]
	v_pk_add_f32 v[100:101], v[100:101], v[100:101] op_sel_hi:[0,1]
	v_pk_add_f32 v[98:99], v[98:99], v[98:99] op_sel_hi:[0,1]
	v_mul_f32_e32 v102, v96, v96
	v_mul_f32_e32 v106, v97, v97
	v_mul_f32_e32 v100, v88, v88
	v_mul_f32_e32 v98, v89, v89
	v_pk_add_f32 v[102:103], v[102:103], v[106:107]
	v_pk_add_f32 v[98:99], v[100:101], v[98:99]
	v_cvt_pk_bf16_f32 v101, v82, v83
	v_pk_add_f32 v[98:99], v[102:103], v[98:99]
	v_cvt_pk_bf16_f32 v102, v92, v93
	v_add_f32_e32 v81, v98, v99
	ds_bpermute_b32 v98, v1, v81
	v_cvt_pk_bf16_f32 v103, v84, v85
	v_cvt_pk_bf16_f32 v105, v86, v87
	v_cvt_pk_bf16_f32 v106, v96, v97
	v_cvt_pk_bf16_f32 v107, v88, v89
	s_waitcnt lgkmcnt(0)
	v_add_f32_e32 v81, v81, v98
	ds_bpermute_b32 v98, v70, v81
	s_waitcnt lgkmcnt(0)
	v_add_f32_e32 v81, v81, v98
	ds_bpermute_b32 v98, v71, v81
	s_waitcnt lgkmcnt(0)
	v_add_f32_e32 v81, v81, v98
	ds_bpermute_b32 v100, v72, v81
	v_add_co_u32_e32 v98, vcc, s9, v66
	s_waitcnt lgkmcnt(0)
	v_add_f32_e32 v81, v81, v100
	ds_bpermute_b32 v104, v73, v81
	v_addc_co_u32_e32 v99, vcc, -1, v67, vcc
	v_cvt_pk_bf16_f32 v100, v90, v91
	s_waitcnt lgkmcnt(0)
	v_add_f32_e32 v81, v81, v104
	ds_bpermute_b32 v108, v74, v81
	v_cvt_pk_bf16_f32 v104, v94, v95
	global_store_dwordx2 v[68:69], v[100:101], off
	global_store_dwordx2 v[68:69], v[102:103], off offset:512
	global_store_dwordx2 v[68:69], v[104:105], off offset:1024
	global_store_dwordx2 v[68:69], v[106:107], off offset:1536
	s_waitcnt lgkmcnt(0)
	v_add_f32_e32 v81, v81, v108
	v_fmamk_f32 v81, v81, 0x3a800000, v79
	v_mul_f32_e32 v108, 0x4f800000, v81
	v_cmp_gt_f32_e32 vcc, s7, v81
	s_nop 1
	v_cndmask_b32_e32 v81, v81, v108, vcc
	v_sqrt_f32_e32 v108, v81
	s_nop 0
	v_add_u32_e32 v100, -1, v108
	v_add_u32_e32 v101, 1, v108
	v_fma_f32 v102, -v100, v108, v81
	v_fma_f32 v103, -v101, v108, v81
	v_cmp_ge_f32_e64 s[0:1], 0, v102
	s_nop 1
	v_cndmask_b32_e64 v100, v108, v100, s[0:1]
	v_cmp_lt_f32_e64 s[0:1], 0, v103
	s_nop 1
	v_cndmask_b32_e64 v100, v100, v101, s[0:1]
	v_mul_f32_e32 v101, 0x37800000, v100
	v_cndmask_b32_e32 v100, v100, v101, vcc
	v_cmp_class_f32_e32 vcc, v81, v80
	s_nop 1
	v_cndmask_b32_e32 v81, v100, v81, vcc
	v_div_scale_f32 v100, s[0:1], v81, v81, 1.0
	v_rcp_f32_e32 v101, v100
	v_div_scale_f32 v68, vcc, 1.0, v81, 1.0
	v_fma_f32 v69, -v100, v101, 1.0
	v_fmac_f32_e32 v101, v69, v101
	v_mul_f32_e32 v69, v68, v101
	v_fma_f32 v102, -v100, v69, v68
	v_fmac_f32_e32 v69, v102, v101
	v_fma_f32 v68, -v100, v69, v68
	v_div_fmas_f32 v68, v68, v101, v69
	v_div_fixup_f32 v68, v68, v81, 1.0
	v_pk_mul_f32 v[90:91], v[90:91], v[68:69] op_sel_hi:[1,0]
	v_pk_mul_f32 v[82:83], v[82:83], v[68:69] op_sel_hi:[1,0]
	v_pk_mul_f32 v[84:85], v[84:85], v[68:69] op_sel_hi:[1,0]
	v_pk_mul_f32 v[92:93], v[92:93], v[68:69] op_sel_hi:[1,0]
	v_pk_fma_f32 v[82:83], v[36:37], v[82:83], v[8:9]
	v_pk_fma_f32 v[90:91], v[34:35], v[90:91], v[6:7]
	v_pk_fma_f32 v[84:85], v[40:41], v[84:85], v[12:13]
	v_pk_fma_f32 v[92:93], v[38:39], v[92:93], v[10:11]
	v_cvt_pk_bf16_f32 v90, v90, v91
	v_cvt_pk_bf16_f32 v91, v82, v83
	v_cvt_pk_bf16_f32 v83, v84, v85
	v_add_co_u32_e32 v84, vcc, s22, v66
	v_cvt_pk_bf16_f32 v82, v92, v93
	s_nop 0
	v_addc_co_u32_e32 v85, vcc, -1, v67, vcc
	global_store_dwordx2 v[84:85], v[82:83], off offset:-3584
	v_pk_mul_f32 v[82:83], v[94:95], v[68:69] op_sel_hi:[1,0]
	v_pk_mul_f32 v[86:87], v[86:87], v[68:69] op_sel_hi:[1,0]
	v_pk_fma_f32 v[82:83], v[42:43], v[82:83], v[2:3]
	v_pk_fma_f32 v[86:87], v[44:45], v[86:87], v[4:5]
	v_cvt_pk_bf16_f32 v82, v82, v83
	v_cvt_pk_bf16_f32 v83, v86, v87
	global_store_dwordx2 v[84:85], v[82:83], off offset:-3072
	v_pk_mul_f32 v[82:83], v[96:97], v[68:69] op_sel_hi:[1,0]
	v_pk_mul_f32 v[68:69], v[88:89], v[68:69] op_sel_hi:[1,0]
	v_pk_fma_f32 v[82:83], v[46:47], v[82:83], v[22:23]
	v_pk_fma_f32 v[68:69], v[48:49], v[68:69], v[24:25]
	v_cvt_pk_bf16_f32 v82, v82, v83
	v_cvt_pk_bf16_f32 v83, v68, v69
	v_lshl_add_u64 v[66:67], v[66:67], 0, s[12:13]
	global_store_dwordx2 v[98:99], v[90:91], off
	global_store_dwordx2 v[84:85], v[82:83], off offset:-2560
	s_cbranch_scc0 .LBB0_907

.LBB0_1065:
	s_cmp_gt_i32 s31, 11
	s_cselect_b64 s[0:1], -1, 0
	s_and_b64 s[4:5], s[6:7], s[0:1]
	s_andn2_b64 vcc, exec, s[4:5]
	s_cbranch_vccnz .LBB0_1125
	s_cmpk_eq_i32 s3, 0x100
	s_cbranch_scc1 .Lls10
	s_waitcnt vmcnt(0)
	s_waitcnt vmcnt(0)
	s_barrier
	s_and_saveexec_b64 s[4:5], s[16:17]
	s_cbranch_execz .LBB0_1124
	s_add_i32 s6, 0, 0x20160
	v_mov_b32_e32 v0, s6
	s_waitcnt vmcnt(0) expcnt(0) lgkmcnt(0)
	ds_read_b32 v2, v0
	s_add_i32 s6, 0, 0x20164
	v_mov_b32_e32 v0, s6
	ds_read_b32 v0, v0
	s_waitcnt lgkmcnt(1)
	v_cmp_ne_u32_e32 vcc, 0, v2
	s_cbranch_vccnz .LBB0_1082
	s_load_dwordx2 s[10:11], s[94:95], 0x4
	s_add_u32 s6, s28, 0x1200
	s_addc_u32 s7, s29, 0
	s_add_u32 s8, s28, 0x1400
	s_addc_u32 s9, s29, 0
	s_waitcnt lgkmcnt(0)
	s_mul_i32 s26, s10, s3
	s_add_u32 s10, s28, 0x1500
	s_mul_i32 s26, s26, s11
	s_addc_u32 s11, s29, 0
	s_add_u32 s12, s28, 0x1600
	s_addc_u32 s13, s29, 0
	s_add_u32 s14, s28, 0x1700
	s_addc_u32 s15, s29, 0
	s_add_u32 s16, s28, 0x1800
	s_addc_u32 s17, s29, 0
	s_add_u32 s18, s28, 0x1900
	s_addc_u32 s19, s29, 0
	s_add_u32 s20, s28, 0x1a00
	s_addc_u32 s21, s29, 0
	s_add_u32 s22, s28, 0x1b00
	s_addc_u32 s23, s29, 0
	s_add_u32 s24, s28, 0x1c00
	s_addc_u32 s25, s29, 0
	s_add_u32 s36, s28, 0x1d00
	s_addc_u32 s37, s29, 0
	s_add_u32 s40, s28, 0x1e00
	s_addc_u32 s41, s29, 0
	s_add_u32 s42, s28, 0x1f00
	s_addc_u32 s43, s29, 0
	s_add_u32 s44, s28, 0x2000
	s_addc_u32 s45, s29, 0
	s_add_u32 s46, s28, 0x2100
	s_addc_u32 s47, s29, 0
	s_add_u32 s48, s28, 0x2200
	s_addc_u32 s49, s29, 0
	s_add_u32 s50, s28, 0x2300
	s_addc_u32 s51, s29, 0
	s_mov_b32 s27, 1
	v_mov_b32_e32 v16, 0
	s_branch .LBB0_1070

.Lls10:
	s_and_b32 s4, s2, 7
	s_lshl_b32 s4, s4, 3
	s_bfe_u32 s5, s2, 0x30003
	s_add_i32 s4, s4, s5
	s_lshl_b32 s4, s4, 6
	s_add_u32 s8, s28, s4
	s_addc_u32 s9, s29, 0
	s_mov_b32 s12, 0
	s_and_saveexec_b64 s[10:11], s[16:17]
	s_cbranch_execz .Lls10_join
	v_mov_b32_e32 v0, 0x8000
	v_mov_b32_e32 v1, 1
	global_atomic_add v0, v1, s[8:9]
.Lls10_spin:
	global_load_dword v2, v0, s[8:9] sc1
	s_waitcnt vmcnt(0)
	v_readfirstlane_b32 s13, v2
	s_add_i32 s12, s12, 1
	s_nop 1
	s_cmp_lt_u32 s13, 4
	s_cbranch_scc0 .Lls10_done
	s_sleep 1
	s_cmp_lt_u32 s12, 0x100000
	s_cbranch_scc1 .Lls10_spin

.LBB0_1125:
	s_cmp_lt_i32 s30, 12
	s_cselect_b64 s[4:5], -1, 0
	s_and_b64 s[0:1], s[4:5], s[0:1]
	s_andn2_b64 vcc, exec, s[0:1]
	s_cbranch_vccnz .LBB0_1131
	s_lshl_b32 s0, s2, 3
	s_add_i32 s99, s33, s0
	s_movk_i32 s98, 0x2800
	s_lshl_b32 s100, s3, 3
	s_cmpk_lg_i32 s3, 0x100
	s_cbranch_scc1 .Lls10_gen
	s_and_b32 s0, s2, 7
	s_lshl_b32 s0, s0, 3
	s_bfe_u32 s1, s2, 0x30003
	s_add_i32 s0, s0, s1
	s_mul_i32 s0, s0, 0xa0
	s_lshr_b32 s1, s2, 6
	s_lshl_b32 s1, s1, 3
	s_add_i32 s99, s0, s1
	s_add_i32 s99, s99, s33
	s_add_i32 s98, s0, 0xa0
	s_mov_b32 s100, 32
.Lls10_gen:
	s_mov_b32 s2, s99
	s_cmpk_gt_i32 s2, 0x27ff
	s_cbranch_scc1 .LBB0_1131
	v_mbcnt_lo_u32_b32 v1, -1, 0
	v_mbcnt_hi_u32_b32 v1, -1, v1
	v_and_b32_e32 v5, 64, v1
	v_add_u32_e32 v5, 64, v5
	v_xor_b32_e32 v7, 1, v1
	v_cmp_lt_i32_e32 vcc, v7, v5
	s_mov_b32 s4, s100
	v_lshlrev_b32_e32 v0, 2, v164
	v_cndmask_b32_e32 v7, v1, v7, vcc
	v_lshlrev_b32_e32 v28, 2, v7
	v_xor_b32_e32 v7, 2, v1
	v_cmp_lt_i32_e32 vcc, v7, v5
	v_mov_b32_e32 v3, 0
	v_or_b32_e32 v4, 0x100, v0
	v_cndmask_b32_e32 v7, v1, v7, vcc
	v_lshlrev_b32_e32 v29, 2, v7
	v_xor_b32_e32 v7, 4, v1
	s_add_u32 s0, s38, 0x2000
	v_cmp_lt_i32_e32 vcc, v7, v5
	v_or_b32_e32 v6, 0x200, v0
	s_addc_u32 s1, s39, 0
	v_lshlrev_b32_e32 v10, 2, v4
	v_mov_b32_e32 v11, v3
	v_cndmask_b32_e32 v7, v1, v7, vcc
	v_or_b32_e32 v8, 0x300, v0
	v_lshl_add_u64 v[18:19], s[0:1], 0, v[10:11]
	v_lshlrev_b32_e32 v10, 2, v6
	v_lshlrev_b32_e32 v30, 2, v7
	v_xor_b32_e32 v7, 8, v1
	v_readlane_b32 s8, v244, 0
	v_lshlrev_b32_e32 v2, 4, v164
	v_lshl_add_u64 v[20:21], s[0:1], 0, v[10:11]
	v_lshlrev_b32_e32 v10, 2, v8
	v_cmp_lt_i32_e32 vcc, v7, v5
	s_ashr_i32 s3, s2, 31
	v_readlane_b32 s10, v244, 2
	v_readlane_b32 s11, v244, 3
	v_readlane_b32 s14, v244, 6
	v_readlane_b32 s15, v244, 7
	v_lshl_add_u64 v[16:17], s[0:1], 0, v[2:3]
	v_lshl_add_u64 v[22:23], s[0:1], 0, v[10:11]
	v_cndmask_b32_e32 v7, v1, v7, vcc
	s_lshl_b64 s[0:1], s[2:3], 12
	s_mov_b64 s[10:11], s[14:15]
	v_lshlrev_b32_e32 v31, 2, v7
	v_xor_b32_e32 v7, 16, v1
	s_add_u32 s0, s10, s0
	v_cmp_lt_i32_e32 vcc, v7, v5
	v_readlane_b32 s9, v244, 1
	s_addc_u32 s1, s11, s1
	s_ashr_i32 s5, s4, 31
	v_cndmask_b32_e32 v7, v1, v7, vcc
	v_lshl_add_u64 v[24:25], s[0:1], 0, v[2:3]
	s_lshl_b64 s[8:9], s[4:5], 12
	s_lshl_b64 s[0:1], s[2:3], 11
	v_lshlrev_b32_e32 v32, 2, v7
	v_xor_b32_e32 v7, 32, v1
	s_add_u32 s0, s28, s0
	v_cmp_lt_i32_e32 vcc, v7, v5
	v_lshlrev_b32_e32 v2, 3, v164
	s_addc_u32 s1, s29, s1
	v_cndmask_b32_e32 v1, v1, v7, vcc
	v_lshl_add_u64 v[2:3], s[0:1], 0, v[2:3]
	s_mov_b64 s[0:1], 0x4500000
	s_mov_b32 s7, 0
	s_mov_b32 s6, -1
	v_lshlrev_b32_e32 v33, 2, v1
	v_lshl_add_u64 v[26:27], v[2:3], 0, s[0:1]
	s_lshl_b64 s[10:11], s[4:5], 11
	s_waitcnt vmcnt(0)
	v_lshlrev_b32_e32 v34, 2, v0
	v_lshlrev_b32_e32 v35, 2, v4
	v_lshlrev_b32_e32 v36, 2, v6
	v_lshlrev_b32_e32 v37, 2, v8
	v_mov_b32_e32 v38, 0x358637bd
	s_mov_b32 s3, 0xf800000
	v_mov_b32_e32 v39, 0x260
	v_readlane_b32 s12, v244, 4
	v_readlane_b32 s13, v244, 5
	s_branch .LBB0_1129
.LBB0_1128:
	global_load_dwordx2 v[40:41], v[26:27], off nt
	global_load_dwordx2 v[42:43], v[26:27], off offset:512 nt
	global_load_dwordx2 v[44:45], v[26:27], off offset:1024 nt
	global_load_dwordx2 v[46:47], v[26:27], off offset:1536 nt
	v_add_co_u32_e32 v48, vcc, 0x2800000, v26
	s_add_i32 s2, s2, s4
	s_nop 0
	v_addc_co_u32_e32 v49, vcc, 0, v27, vcc
	global_load_dwordx2 v[50:51], v[48:49], off nt
	global_load_dwordx2 v[52:53], v[48:49], off offset:512 nt
	global_load_dwordx2 v[54:55], v[48:49], off offset:1024 nt
	global_load_dwordx2 v[56:57], v[48:49], off offset:1536 nt
	s_cmp_lt_i32 s2, s98
	v_lshl_add_u64 v[26:27], v[26:27], 0, s[10:11]
	s_waitcnt vmcnt(7)
	v_lshlrev_b32_e32 v48, 16, v40
	v_and_b32_e32 v49, 0xffff0000, v40
	v_lshlrev_b32_e32 v40, 16, v41
	v_and_b32_e32 v41, 0xffff0000, v41
	s_waitcnt vmcnt(6)
	v_lshlrev_b32_e32 v59, 16, v43
	v_lshlrev_b32_e32 v58, 16, v42
	v_and_b32_e32 v43, 0xffff0000, v43
	v_and_b32_e32 v42, 0xffff0000, v42
	s_waitcnt vmcnt(5)
	v_and_b32_e32 v61, 0xffff0000, v44
	s_waitcnt vmcnt(4)
	v_lshlrev_b32_e32 v63, 16, v46
	v_and_b32_e32 v65, 0xffff0000, v46
	v_mul_f32_e32 v62, v41, v41
	v_mul_f32_e32 v64, v49, v49
	v_lshlrev_b32_e32 v60, 16, v44
	v_lshlrev_b32_e32 v44, 16, v45
	v_and_b32_e32 v45, 0xffff0000, v45
	v_pk_mul_f32 v[66:67], v[42:43], v[42:43]
	v_mov_b32_e32 v69, v63
	v_mul_f32_e32 v68, v61, v61
	v_pk_fma_f32 v[72:73], v[40:41], v[40:41], v[62:63] op_sel_hi:[1,1,0]
	v_pk_fma_f32 v[74:75], v[48:49], v[48:49], v[64:65] op_sel_hi:[1,1,0]
	v_lshlrev_b32_e32 v46, 16, v47
	v_and_b32_e32 v47, 0xffff0000, v47
	v_mul_f32_e32 v70, v45, v45
	v_pk_fma_f32 v[66:67], v[58:59], v[58:59], v[66:67]
	v_pk_fma_f32 v[76:77], v[60:61], v[60:61], v[68:69] op_sel_hi:[1,1,0]
	v_mov_b32_e32 v62, v74
	v_mov_b32_e32 v68, v72
	v_mul_f32_e32 v78, v65, v65
	v_mul_f32_e32 v79, v46, v46
	v_mul_f32_e32 v80, v47, v47
	v_pk_fma_f32 v[70:71], v[44:45], v[44:45], v[70:71] op_sel_hi:[1,1,0]
	v_pk_add_f32 v[72:73], v[74:75], v[72:73]
	v_pk_add_f32 v[66:67], v[66:67], v[66:67] op_sel:[0,1] op_sel_hi:[1,0]
	v_pk_mul_f32 v[68:69], v[62:63], v[68:69]
	v_mov_b32_e32 v77, v79
	v_mov_b32_e32 v71, v80
	v_mov_b32_e32 v67, v78
	v_mov_b32_e32 v73, v69
	v_pk_add_f32 v[70:71], v[76:77], v[70:71]
	v_pk_add_f32 v[66:67], v[72:73], v[66:67]
	s_nop 0
	v_pk_add_f32 v[66:67], v[66:67], v[70:71]
	s_nop 0
	v_add_f32_e32 v62, v66, v67
	ds_bpermute_b32 v64, v28, v62
	v_mov_b32_e32 v66, v58
	v_mov_b32_e32 v67, v42
	v_mov_b32_e32 v42, v59
	s_waitcnt vmcnt(3)
	v_lshlrev_b32_e32 v58, 16, v50
	s_waitcnt lgkmcnt(0)
	v_add_f32_e32 v62, v62, v64
	ds_bpermute_b32 v64, v29, v62
	v_and_b32_e32 v59, 0xffff0000, v50
	v_lshlrev_b32_e32 v50, 16, v51
	v_and_b32_e32 v51, 0xffff0000, v51
	s_waitcnt lgkmcnt(0)
	v_add_f32_e32 v62, v62, v64
	ds_bpermute_b32 v68, v30, v62
	v_mov_b32_e32 v64, v63
	s_waitcnt lgkmcnt(0)
	v_add_f32_e32 v62, v62, v68
	ds_bpermute_b32 v63, v31, v62
	s_waitcnt lgkmcnt(0)
	v_add_f32_e32 v68, v62, v63
	ds_bpermute_b32 v69, v32, v68
	s_waitcnt vmcnt(2)
	v_lshlrev_b32_e32 v62, 16, v52
	v_and_b32_e32 v63, 0xffff0000, v52
	v_lshlrev_b32_e32 v52, 16, v53
	v_and_b32_e32 v53, 0xffff0000, v53
	s_waitcnt lgkmcnt(0)
	v_add_f32_e32 v70, v68, v69
	ds_bpermute_b32 v71, v33, v70
	s_waitcnt vmcnt(1)
	v_lshlrev_b32_e32 v68, 16, v54
	v_and_b32_e32 v69, 0xffff0000, v54
	v_lshlrev_b32_e32 v54, 16, v55
	v_and_b32_e32 v55, 0xffff0000, v55
	s_waitcnt lgkmcnt(0)
	v_add_f32_e32 v70, v70, v71
	v_fmamk_f32 v70, v70, 0x3a800000, v38
	v_mul_f32_e32 v71, 0x4f800000, v70
	v_cmp_gt_f32_e32 vcc, s3, v70
	s_nop 1
	v_cndmask_b32_e32 v72, v70, v71, vcc
	v_sqrt_f32_e32 v73, v72
	s_waitcnt vmcnt(0)
	v_lshlrev_b32_e32 v70, 16, v56
	v_and_b32_e32 v71, 0xffff0000, v56
	v_lshlrev_b32_e32 v56, 16, v57
	v_add_u32_e32 v74, -1, v73
	v_add_u32_e32 v75, 1, v73
	v_fma_f32 v76, -v74, v73, v72
	v_fma_f32 v77, -v75, v73, v72
	v_cmp_ge_f32_e64 s[0:1], 0, v76
	v_and_b32_e32 v57, 0xffff0000, v57
	s_nop 0
	v_cndmask_b32_e64 v73, v73, v74, s[0:1]
	v_cmp_lt_f32_e64 s[0:1], 0, v77
	s_nop 1
	v_cndmask_b32_e64 v73, v73, v75, s[0:1]
	v_mul_f32_e32 v74, 0x37800000, v73
	v_cndmask_b32_e32 v73, v73, v74, vcc
	v_cmp_class_f32_e32 vcc, v72, v39
	s_nop 1
	v_cndmask_b32_e32 v72, v73, v72, vcc
	v_div_scale_f32 v73, s[0:1], v72, v72, 1.0
	v_rcp_f32_e32 v74, v73
	v_div_scale_f32 v75, vcc, 1.0, v72, 1.0
	v_fma_f32 v76, -v73, v74, 1.0
	v_fmac_f32_e32 v74, v76, v74
	v_mul_f32_e32 v76, v75, v74
	v_fma_f32 v77, -v73, v76, v75
	v_fmac_f32_e32 v76, v77, v74
	v_fma_f32 v73, -v73, v76, v75
	v_div_fmas_f32 v73, v73, v74, v76
	v_div_fixup_f32 v72, v73, v72, 1.0
	v_pk_mul_f32 v[48:49], v[72:73], v[48:49] op_sel_hi:[0,1]
	v_pk_mul_f32 v[40:41], v[72:73], v[40:41] op_sel_hi:[0,1]
	v_pk_mul_f32 v[66:67], v[72:73], v[66:67] op_sel_hi:[0,1]
	v_pk_mul_f32 v[74:75], v[72:73], v[42:43] op_sel_hi:[0,1]
	v_pk_mul_f32 v[60:61], v[72:73], v[60:61] op_sel_hi:[0,1]
	v_pk_mul_f32 v[76:77], v[72:73], v[44:45] op_sel_hi:[0,1]
	v_pk_mul_f32 v[64:65], v[64:65], v[72:73] op_sel_hi:[1,0]
	v_pk_mul_f32 v[72:73], v[46:47], v[72:73] op_sel_hi:[1,0]
	v_pk_fma_f32 v[42:43], v[2:3], v[40:41], v[50:51]
	v_pk_fma_f32 v[40:41], v[0:1], v[48:49], v[58:59]
	v_pk_fma_f32 v[46:47], v[6:7], v[74:75], v[52:53]
	v_pk_fma_f32 v[44:45], v[4:5], v[66:67], v[62:63]
	v_pk_fma_f32 v[50:51], v[10:11], v[76:77], v[54:55]
	v_pk_fma_f32 v[48:49], v[8:9], v[60:61], v[68:69]
	v_pk_fma_f32 v[54:55], v[14:15], v[72:73], v[56:57]
	v_pk_fma_f32 v[52:53], v[12:13], v[64:65], v[70:71]
	global_store_dwordx4 v[24:25], v[40:43], off
	global_store_dwordx4 v[24:25], v[44:47], off offset:1024
	global_store_dwordx4 v[24:25], v[48:51], off offset:2048
	global_store_dwordx4 v[24:25], v[52:55], off offset:3072
	v_lshl_add_u64 v[24:25], v[24:25], 0, s[8:9]
	s_cbranch_scc0 .LBB0_1131
